# mixer C attention inner loop rescheduled: V fragments prefetched at loop top, early output rescale, PV MFMAs issued under the exp chain
# speedup vs baseline: 1.0884x; 1.0042x over previous
.LBB0_552:
	v_cndmask_b32_e64 v2, 0, 1, s[0:1]
	s_mul_i32 s0, s4, 0x2400
	v_add_u32_e32 v11, s0, v175
	v_cmp_ne_u32_e32 vcc, 1, v2
	ds_read_b128 v[2:5], v11
	ds_read_b128 v[12:15], v11 offset:4608
	ds_read_b128 v[6:9], v11 offset:32
	ds_read_b128 v[124:127], v11 offset:4640
	v_lshl_add_u32 v110, s4, 7, v174
	v_add_u32_e32 v111, 0x4800, v110
	v_add_u32_e32 v110, 0x6800, v110
	ds_read2_b64 v[82:85], v111 offset1:2
	ds_read2_b64 v[86:89], v110 offset0:64 offset1:66
	ds_read2_b64 v[90:93], v111 offset0:4 offset1:6
	ds_read2_b64 v[94:97], v110 offset0:68 offset1:70
	ds_read2_b64 v[98:101], v111 offset0:8 offset1:10
	ds_read2_b64 v[102:105], v110 offset0:72 offset1:74
	ds_read2_b64 v[106:109], v111 offset0:12 offset1:14
	ds_read2_b64 v[120:123], v110 offset0:76 offset1:78
	v_mov_b32_e32 v10, v164
	v_mov_b32_e32 v80, v165
	s_and_b64 vcc, exec, vcc
	s_waitcnt lgkmcnt(11)
	v_mfma_f32_32x32x16_bf16 v[64:79], v[2:5], v[112:115], 0
	s_waitcnt lgkmcnt(10)
	v_mfma_f32_32x32x16_bf16 v[48:63], v[12:15], v[112:115], 0
	s_waitcnt lgkmcnt(9)
	v_mfma_f32_32x32x16_bf16 v[64:79], v[6:9], v[116:119], v[64:79]
	s_waitcnt lgkmcnt(8)
	v_mfma_f32_32x32x16_bf16 v[48:63], v[124:127], v[116:119], v[48:63]
	s_nop 9
	v_max3_f32 v2, v64, s61, v65
	v_max3_f32 v2, v2, v66, v67
	v_max3_f32 v2, v2, v68, v69
	v_max3_f32 v2, v2, v70, v71
	v_max3_f32 v2, v2, v72, v73
	v_max3_f32 v2, v2, v74, v75
	v_max3_f32 v2, v2, v76, v77
	v_max3_f32 v2, v2, v78, v79
	v_max3_f32 v2, v2, v48, v49
	v_max3_f32 v2, v2, v50, v51
	v_max3_f32 v2, v2, v52, v53
	v_max3_f32 v2, v2, v54, v55
	v_max3_f32 v2, v2, v56, v57
	v_max3_f32 v2, v2, v58, v59
	v_max3_f32 v2, v2, v60, v61
	v_max3_f32 v2, v2, v62, v63
	v_mul_f32_e32 v2, s9, v2
	ds_bpermute_b32 v3, v0, v2
	s_waitcnt lgkmcnt(0)
	v_max3_f32 v164, v10, v2, v3
	v_cmp_eq_f32_e64 s[0:1], s61, v164
	v_sub_f32_e32 v2, v10, v164
	v_exp_f32_e32 v2, v2
	v_cndmask_b32_e64 v3, v164, 0, s[0:1]
	v_cndmask_b32_e64 v110, v2, 1.0, s[0:1]
	v_pk_mul_f32 v[46:47], v[46:47], v[110:111] op_sel_hi:[1,0]
	v_pk_mul_f32 v[44:45], v[44:45], v[110:111] op_sel_hi:[1,0]
	v_pk_mul_f32 v[42:43], v[42:43], v[110:111] op_sel_hi:[1,0]
	v_pk_mul_f32 v[40:41], v[40:41], v[110:111] op_sel_hi:[1,0]
	v_pk_mul_f32 v[38:39], v[38:39], v[110:111] op_sel_hi:[1,0]
	v_pk_mul_f32 v[36:37], v[36:37], v[110:111] op_sel_hi:[1,0]
	v_pk_mul_f32 v[34:35], v[34:35], v[110:111] op_sel_hi:[1,0]
	v_pk_mul_f32 v[32:33], v[32:33], v[110:111] op_sel_hi:[1,0]
	v_pk_mul_f32 v[30:31], v[30:31], v[110:111] op_sel_hi:[1,0]
	v_pk_mul_f32 v[28:29], v[28:29], v[110:111] op_sel_hi:[1,0]
	v_pk_mul_f32 v[26:27], v[26:27], v[110:111] op_sel_hi:[1,0]
	v_pk_mul_f32 v[24:25], v[24:25], v[110:111] op_sel_hi:[1,0]
	v_pk_mul_f32 v[22:23], v[22:23], v[110:111] op_sel_hi:[1,0]
	v_pk_mul_f32 v[20:21], v[20:21], v[110:111] op_sel_hi:[1,0]
	v_pk_mul_f32 v[18:19], v[18:19], v[110:111] op_sel_hi:[1,0]
	v_pk_mul_f32 v[16:17], v[16:17], v[110:111] op_sel_hi:[1,0]
	s_mov_b64 s[0:1], 0
	s_mov_b32 s4, 1
	v_fma_f32 v4, s9, v64, -v3
	v_exp_f32_e32 v4, v4
	v_fma_f32 v6, s9, v65, -v3
	v_exp_f32_e32 v64, v6
	v_fma_f32 v6, s9, v66, -v3
	v_exp_f32_e32 v65, v6
	v_fma_f32 v6, s9, v67, -v3
	v_exp_f32_e32 v66, v6
	v_fma_f32 v6, s9, v68, -v3
	v_add_f32_e32 v5, 0, v4
	v_exp_f32_e32 v67, v6
	v_fma_f32 v6, s9, v69, -v3
	v_add_f32_e32 v5, v64, v5
	v_exp_f32_e32 v68, v6
	v_fma_f32 v6, s9, v70, -v3
	v_add_f32_e32 v5, v65, v5
	v_exp_f32_e32 v69, v6
	v_fma_f32 v6, s9, v71, -v3
	v_add_f32_e32 v5, v66, v5
	v_exp_f32_e32 v70, v6
	v_fma_f32 v6, s9, v72, -v3
	v_add_f32_e32 v5, v67, v5
	v_cvt_pk_bf16_f32 v124, v4, v64
	v_cvt_pk_bf16_f32 v125, v65, v66
	v_cvt_pk_bf16_f32 v126, v67, v68
	v_cvt_pk_bf16_f32 v127, v69, v70
	s_nop 1
	v_mfma_f32_32x32x16_bf16 v[32:47], v[82:85], v[124:127], v[32:47]
	v_mfma_f32_32x32x16_bf16 v[16:31], v[86:89], v[124:127], v[16:31]
	v_exp_f32_e32 v6, v6
	v_fma_f32 v7, s9, v73, -v3
	v_add_f32_e32 v5, v68, v5
	v_exp_f32_e32 v7, v7
	v_fma_f32 v8, s9, v74, -v3
	v_add_f32_e32 v5, v69, v5
	v_exp_f32_e32 v8, v8
	v_fma_f32 v9, s9, v75, -v3
	v_add_f32_e32 v5, v70, v5
	v_exp_f32_e32 v9, v9
	v_fma_f32 v10, s9, v76, -v3
	v_add_f32_e32 v5, v6, v5
	v_exp_f32_e32 v10, v10
	v_fma_f32 v11, s9, v77, -v3
	v_add_f32_e32 v5, v7, v5
	v_exp_f32_e32 v11, v11
	v_fma_f32 v12, s9, v78, -v3
	v_add_f32_e32 v5, v8, v5
	v_exp_f32_e32 v12, v12
	v_fma_f32 v13, s9, v79, -v3
	v_add_f32_e32 v5, v9, v5
	v_exp_f32_e32 v14, v13
	v_fma_f32 v13, s9, v48, -v3
	v_add_f32_e32 v5, v10, v5
	v_cvt_pk_bf16_f32 v124, v6, v7
	v_cvt_pk_bf16_f32 v125, v8, v9
	v_cvt_pk_bf16_f32 v126, v10, v11
	v_cvt_pk_bf16_f32 v127, v12, v14
	s_nop 1
	v_mfma_f32_32x32x16_bf16 v[32:47], v[90:93], v[124:127], v[32:47]
	v_mfma_f32_32x32x16_bf16 v[16:31], v[94:97], v[124:127], v[16:31]
	v_exp_f32_e32 v13, v13
	v_fma_f32 v15, s9, v49, -v3
	v_add_f32_e32 v5, v11, v5
	v_exp_f32_e32 v15, v15
	v_fma_f32 v48, s9, v50, -v3
	v_add_f32_e32 v5, v12, v5
	v_exp_f32_e32 v48, v48
	v_fma_f32 v49, s9, v51, -v3
	v_add_f32_e32 v5, v14, v5
	v_exp_f32_e32 v49, v49
	v_fma_f32 v50, s9, v52, -v3
	v_add_f32_e32 v5, v13, v5
	v_exp_f32_e32 v50, v50
	v_fma_f32 v51, s9, v53, -v3
	v_add_f32_e32 v5, v15, v5
	v_exp_f32_e32 v51, v51
	v_fma_f32 v52, s9, v54, -v3
	v_add_f32_e32 v5, v48, v5
	v_exp_f32_e32 v52, v52
	v_fma_f32 v53, s9, v55, -v3
	v_add_f32_e32 v5, v49, v5
	v_exp_f32_e32 v54, v53
	v_fma_f32 v53, s9, v56, -v3
	v_add_f32_e32 v5, v50, v5
	v_cvt_pk_bf16_f32 v124, v13, v15
	v_cvt_pk_bf16_f32 v125, v48, v49
	v_cvt_pk_bf16_f32 v126, v50, v51
	v_cvt_pk_bf16_f32 v127, v52, v54
	s_nop 1
	v_mfma_f32_32x32x16_bf16 v[32:47], v[98:101], v[124:127], v[32:47]
	v_mfma_f32_32x32x16_bf16 v[16:31], v[102:105], v[124:127], v[16:31]
	v_exp_f32_e32 v53, v53
	v_fma_f32 v55, s9, v57, -v3
	v_add_f32_e32 v5, v51, v5
	v_exp_f32_e32 v55, v55
	v_fma_f32 v56, s9, v58, -v3
	v_add_f32_e32 v5, v52, v5
	v_exp_f32_e32 v56, v56
	v_fma_f32 v57, s9, v59, -v3
	v_add_f32_e32 v5, v54, v5
	v_exp_f32_e32 v57, v57
	v_fma_f32 v58, s9, v60, -v3
	v_add_f32_e32 v5, v53, v5
	v_exp_f32_e32 v58, v58
	v_fma_f32 v59, s9, v61, -v3
	v_add_f32_e32 v5, v55, v5
	v_exp_f32_e32 v59, v59
	v_fma_f32 v60, s9, v62, -v3
	v_add_f32_e32 v5, v56, v5
	v_exp_f32_e32 v60, v60
	v_fma_f32 v3, s9, v63, -v3
	v_add_f32_e32 v5, v57, v5
	v_exp_f32_e32 v61, v3
	v_add_f32_e32 v5, v58, v5
	v_add_f32_e32 v5, v59, v5
	v_add_f32_e32 v5, v60, v5
	v_add_f32_e32 v165, v61, v5
	v_cvt_pk_bf16_f32 v124, v53, v55
	v_cvt_pk_bf16_f32 v125, v56, v57
	v_cvt_pk_bf16_f32 v126, v58, v59
	v_cvt_pk_bf16_f32 v127, v60, v61
	v_fmac_f32_e32 v165, v80, v110
	s_nop 0
	v_mfma_f32_32x32x16_bf16 v[32:47], v[106:109], v[124:127], v[32:47]
	v_mfma_f32_32x32x16_bf16 v[16:31], v[120:123], v[124:127], v[16:31]
	s_cbranch_vccz .LBB0_552
	s_nop 9
	v_mov_b64_e32 v[62:63], v[46:47]
	s_nop 1
	v_mov_b64_e32 v[78:79], v[30:31]
	v_mov_b64_e32 v[60:61], v[44:45]
	v_mov_b64_e32 v[58:59], v[42:43]
	v_mov_b64_e32 v[56:57], v[40:41]
	v_mov_b64_e32 v[54:55], v[38:39]
	v_mov_b64_e32 v[52:53], v[36:37]
	v_mov_b64_e32 v[50:51], v[34:35]
	v_mov_b64_e32 v[48:49], v[32:33]
	v_mov_b64_e32 v[76:77], v[28:29]
	v_mov_b64_e32 v[74:75], v[26:27]
	v_mov_b64_e32 v[72:73], v[24:25]
	v_mov_b64_e32 v[70:71], v[22:23]
	v_mov_b64_e32 v[68:69], v[20:21]
	v_mov_b64_e32 v[66:67], v[18:19]
	v_mov_b64_e32 v[64:65], v[16:17]
	v_mov_b32_e32 v7, v164
	v_mov_b32_e32 v8, v165
